# barrier XCD leader: acquire invalidate issued before its L2 write-back so it hides under the write-back wait instead of lengthening the top-level arrival
# baseline (speedup 1.0000x reference)
; __device__ __forceinline__ unsigned xb_add(unsigned* p, unsigned v) { return __hip_atomic_fetch_add(p, v, __ATOMIC_RELAXED, __HIP_MEMORY_SCOPE_AGENT); }
; __device__ __forceinline__ void xcd_barrier(const XcdBarrier& b) {
;     ...
;         const unsigned old = xb_add(&bar[XB_XSUB(b.x)], 1u);
;         const unsigned gen = old / nloc;
;         if (old + 1u == (gen + 1u) * nloc) {
;             __builtin_amdgcn_fence(__ATOMIC_RELEASE, "agent");
;             asm volatile("s_waitcnt vmcnt(0)" ::: "memory");
;             const unsigned og = xb_add(&bar[XB_TOP], 1u);
;             const unsigned tg = og / nx;
;             if (og + 1u == (tg + 1u) * nx) xb_add(&bar[XB_TOPGEN], 1u);
.LBB0_447:
	s_andn2_saveexec_b64 s[6:7], s[6:7]
	s_cbranch_execz .LBB0_467
	s_mov_b64 s[6:7], exec
	buffer_inv sc1
	buffer_wbl2 sc1
	s_waitcnt lgkmcnt(0)
	s_waitcnt vmcnt(0)
	v_mbcnt_lo_u32_b32 v1, s6, 0
	v_mbcnt_hi_u32_b32 v1, s7, v1
	v_cmp_eq_u32_e32 vcc, 0, v1
	s_and_saveexec_b64 s[8:9], vcc
	s_cbranch_execz .LBB0_450
	s_bcnt1_i32_b64 s6, s[6:7]
	v_mov_b32_e32 v3, s6
	v_readlane_b32 s6, v240, 32
	v_mov_b32_e32 v2, 0
	v_readlane_b32 s7, v240, 33
	s_nop 4
	global_atomic_add v2, v2, v3, s[6:7] sc0

; __device__ __forceinline__ unsigned xb_add(unsigned* p, unsigned v) { return __hip_atomic_fetch_add(p, v, __ATOMIC_RELAXED, __HIP_MEMORY_SCOPE_AGENT); }
; __device__ __forceinline__ void xcd_barrier(const XcdBarrier& b) {
;     ...
;         const unsigned old = xb_add(&bar[XB_XSUB(b.x)], 1u);
;         const unsigned gen = old / nloc;
;         if (old + 1u == (gen + 1u) * nloc) {
;             __builtin_amdgcn_fence(__ATOMIC_RELEASE, "agent");
;             asm volatile("s_waitcnt vmcnt(0)" ::: "memory");
;             const unsigned og = xb_add(&bar[XB_TOP], 1u);
;             const unsigned tg = og / nx;
;             if (og + 1u == (tg + 1u) * nx) xb_add(&bar[XB_TOPGEN], 1u);
.LBB0_621:
	s_andn2_saveexec_b64 s[8:9], s[8:9]
	s_cbranch_execz .LBB0_641
	s_mov_b64 s[8:9], exec
	buffer_inv sc1
	buffer_wbl2 sc1
	s_waitcnt lgkmcnt(0)
	s_waitcnt vmcnt(0)
	v_mbcnt_lo_u32_b32 v1, s8, 0
	v_mbcnt_hi_u32_b32 v1, s9, v1
	v_cmp_eq_u32_e32 vcc, 0, v1
	s_and_saveexec_b64 s[10:11], vcc
	s_cbranch_execz .LBB0_624
	s_bcnt1_i32_b64 s8, s[8:9]
	v_mov_b32_e32 v3, s8
	v_readlane_b32 s8, v240, 32
	v_mov_b32_e32 v2, 0
	v_readlane_b32 s9, v240, 33
	s_nop 4
	global_atomic_add v2, v2, v3, s[8:9] sc0

; __device__ __forceinline__ unsigned xb_add(unsigned* p, unsigned v) { return __hip_atomic_fetch_add(p, v, __ATOMIC_RELAXED, __HIP_MEMORY_SCOPE_AGENT); }
; __device__ __forceinline__ void xcd_barrier(const XcdBarrier& b) {
;     ...
;         const unsigned old = xb_add(&bar[XB_XSUB(b.x)], 1u);
;         const unsigned gen = old / nloc;
;         if (old + 1u == (gen + 1u) * nloc) {
;             __builtin_amdgcn_fence(__ATOMIC_RELEASE, "agent");
;             asm volatile("s_waitcnt vmcnt(0)" ::: "memory");
;             const unsigned og = xb_add(&bar[XB_TOP], 1u);
;             const unsigned tg = og / nx;
;             if (og + 1u == (tg + 1u) * nx) xb_add(&bar[XB_TOPGEN], 1u);
.LBB0_1032:
	s_andn2_saveexec_b64 s[4:5], s[4:5]
	s_cbranch_execz .LBB0_1052
	s_mov_b64 s[4:5], exec
	buffer_inv sc1
	buffer_wbl2 sc1
	s_waitcnt lgkmcnt(0)
	s_waitcnt vmcnt(0)
	v_mbcnt_lo_u32_b32 v1, s4, 0
	v_mbcnt_hi_u32_b32 v1, s5, v1
	v_cmp_eq_u32_e32 vcc, 0, v1
	s_and_saveexec_b64 s[6:7], vcc
	s_cbranch_execz .LBB0_1035
	s_bcnt1_i32_b64 s4, s[4:5]
	v_mov_b32_e32 v3, s4
	v_readlane_b32 s4, v240, 32
	v_mov_b32_e32 v2, 0
	v_readlane_b32 s5, v240, 33
	s_nop 4
	global_atomic_add v2, v2, v3, s[4:5] sc0

; __device__ __forceinline__ unsigned xb_add(unsigned* p, unsigned v) { return __hip_atomic_fetch_add(p, v, __ATOMIC_RELAXED, __HIP_MEMORY_SCOPE_AGENT); }
; __device__ __forceinline__ void xcd_barrier(const XcdBarrier& b) {
;     ...
;         const unsigned old = xb_add(&bar[XB_XSUB(b.x)], 1u);
;         const unsigned gen = old / nloc;
;         if (old + 1u == (gen + 1u) * nloc) {
;             __builtin_amdgcn_fence(__ATOMIC_RELEASE, "agent");
;             asm volatile("s_waitcnt vmcnt(0)" ::: "memory");
;             const unsigned og = xb_add(&bar[XB_TOP], 1u);
;             const unsigned tg = og / nx;
;             if (og + 1u == (tg + 1u) * nx) xb_add(&bar[XB_TOPGEN], 1u);
.LBB0_1371:
	s_andn2_saveexec_b64 s[2:3], s[2:3]
	s_cbranch_execz .LBB0_1391
	s_mov_b64 s[2:3], exec
	buffer_inv sc1
	buffer_wbl2 sc1
	s_waitcnt lgkmcnt(0)
	s_waitcnt vmcnt(0)
	v_mbcnt_lo_u32_b32 v1, s2, 0
	v_mbcnt_hi_u32_b32 v1, s3, v1
	v_cmp_eq_u32_e32 vcc, 0, v1
	s_and_saveexec_b64 s[4:5], vcc
	s_cbranch_execz .LBB0_1374
	s_bcnt1_i32_b64 s2, s[2:3]
	v_mov_b32_e32 v3, s2
	v_readlane_b32 s2, v240, 32
	v_mov_b32_e32 v2, 0
	v_readlane_b32 s3, v240, 33
	s_nop 4
	global_atomic_add v2, v2, v3, s[2:3] sc0
